# v49 + weight-conversion transposed LDS reads issued up front with counted waits
# baseline (speedup 1.0000x reference)
.LBB0_16:
	s_lshl_b32 s22, s9, 1
	s_lshl_b32 s23, s20, 1
	v_or_b32_e32 v0, s22, v3
	v_or_b32_e32 v33, s23, v2
	s_add_i32 s24, s22, 4
	s_add_i32 s25, s23, 4
	s_add_i32 s26, s22, 8
	s_add_i32 s27, s23, 8
	s_add_i32 s28, s22, 12
	s_add_i32 s29, s23, 12
	s_add_i32 s30, s22, 16
	s_add_i32 s31, s23, 16
	s_add_i32 s34, s22, 20
	s_add_i32 s35, s23, 20
	s_add_i32 s36, s22, 24
	s_add_i32 s37, s23, 24
	s_add_i32 s22, s22, 28
	s_add_i32 s23, s23, 28
	v_add_u32_e32 v36, s8, v33
	v_or_b32_e32 v66, s24, v3
	v_or_b32_e32 v67, s25, v2
	v_or_b32_e32 v68, s26, v3
	v_or_b32_e32 v69, s27, v2
	v_or_b32_e32 v70, s28, v3
	v_or_b32_e32 v71, s29, v2
	v_or_b32_e32 v72, s30, v3
	v_or_b32_e32 v73, s31, v2
	v_or_b32_e32 v74, s34, v3
	v_or_b32_e32 v75, s35, v2
	v_or_b32_e32 v76, s36, v3
	v_or_b32_e32 v77, s37, v2
	v_or_b32_e32 v78, s22, v3
	v_or_b32_e32 v79, s23, v2
	v_add_u32_e32 v34, s19, v0
	v_ashrrev_i32_e32 v37, 31, v36
	v_add_u32_e32 v38, s19, v66
	v_add_u32_e32 v40, s8, v67
	v_add_u32_e32 v42, s19, v68
	v_add_u32_e32 v44, s8, v69
	v_add_u32_e32 v46, s19, v70
	v_add_u32_e32 v48, s8, v71
	v_add_u32_e32 v50, s19, v72
	v_add_u32_e32 v52, s8, v73
	v_add_u32_e32 v54, s19, v74
	v_add_u32_e32 v56, s8, v75
	v_add_u32_e32 v58, s19, v76
	v_add_u32_e32 v60, s8, v77
	v_add_u32_e32 v62, s19, v78
	v_add_u32_e32 v64, s8, v79
	v_ashrrev_i32_e32 v35, 31, v34
	v_lshlrev_b64 v[36:37], 12, v[36:37]
	v_ashrrev_i32_e32 v41, 31, v40
	v_ashrrev_i32_e32 v39, 31, v38
	v_ashrrev_i32_e32 v45, 31, v44
	v_ashrrev_i32_e32 v43, 31, v42
	v_ashrrev_i32_e32 v49, 31, v48
	v_ashrrev_i32_e32 v47, 31, v46
	v_ashrrev_i32_e32 v53, 31, v52
	v_ashrrev_i32_e32 v51, 31, v50
	v_ashrrev_i32_e32 v57, 31, v56
	v_ashrrev_i32_e32 v55, 31, v54
	v_ashrrev_i32_e32 v61, 31, v60
	v_ashrrev_i32_e32 v59, 31, v58
	v_ashrrev_i32_e32 v65, 31, v64
	v_ashrrev_i32_e32 v63, 31, v62
	v_lshlrev_b64 v[34:35], 12, v[34:35]
	v_lshl_add_u64 v[36:37], v[28:29], 0, v[36:37]
	v_lshlrev_b64 v[38:39], 12, v[38:39]
	v_lshlrev_b64 v[40:41], 12, v[40:41]
	v_lshlrev_b64 v[42:43], 12, v[42:43]
	v_lshlrev_b64 v[44:45], 12, v[44:45]
	v_lshlrev_b64 v[46:47], 12, v[46:47]
	v_lshlrev_b64 v[48:49], 12, v[48:49]
	v_lshlrev_b64 v[50:51], 12, v[50:51]
	v_lshlrev_b64 v[52:53], 12, v[52:53]
	v_lshlrev_b64 v[54:55], 12, v[54:55]
	v_lshlrev_b64 v[56:57], 12, v[56:57]
	v_lshlrev_b64 v[58:59], 12, v[58:59]
	v_lshlrev_b64 v[60:61], 12, v[60:61]
	v_lshlrev_b64 v[62:63], 12, v[62:63]
	v_lshlrev_b64 v[64:65], 12, v[64:65]
	v_lshl_add_u64 v[34:35], v[28:29], 0, v[34:35]
	v_lshl_add_u64 v[40:41], v[28:29], 0, v[40:41]
	v_lshl_add_u64 v[38:39], v[28:29], 0, v[38:39]
	v_lshl_add_u64 v[44:45], v[28:29], 0, v[44:45]
	v_lshl_add_u64 v[42:43], v[28:29], 0, v[42:43]
	v_lshl_add_u64 v[48:49], v[28:29], 0, v[48:49]
	v_lshl_add_u64 v[46:47], v[28:29], 0, v[46:47]
	v_lshl_add_u64 v[52:53], v[28:29], 0, v[52:53]
	v_lshl_add_u64 v[50:51], v[28:29], 0, v[50:51]
	v_lshl_add_u64 v[56:57], v[28:29], 0, v[56:57]
	v_lshl_add_u64 v[54:55], v[28:29], 0, v[54:55]
	v_lshl_add_u64 v[60:61], v[28:29], 0, v[60:61]
	v_lshl_add_u64 v[58:59], v[28:29], 0, v[58:59]
	v_lshl_add_u64 v[64:65], v[28:29], 0, v[64:65]
	v_lshl_add_u64 v[62:63], v[28:29], 0, v[62:63]
	global_load_dword v80, v[36:37], off
	global_load_dword v81, v[34:35], off
	global_load_dword v82, v[40:41], off
	global_load_dword v83, v[38:39], off
	global_load_dword v84, v[44:45], off
	global_load_dword v85, v[42:43], off
	global_load_dword v86, v[48:49], off
	global_load_dword v87, v[46:47], off
	global_load_dword v88, v[52:53], off
	global_load_dword v89, v[50:51], off
	global_load_dword v90, v[56:57], off
	global_load_dword v91, v[54:55], off
	global_load_dword v92, v[60:61], off
	global_load_dword v93, v[58:59], off
	global_load_dword v94, v[64:65], off
	global_load_dword v95, v[62:63], off
	s_add_i32 s20, s20, 16
	s_add_i32 s9, s9, 16
	s_add_i32 s21, s21, -16
	v_mad_u64_u32 v[34:35], s[22:23], v33, s51, v[16:17]
	s_cmp_lg_u32 s21, 0
	v_mad_u64_u32 v[36:37], s[22:23], v0, s51, v[16:17]
	v_mad_u64_u32 v[38:39], s[22:23], v67, s51, v[16:17]
	v_mad_u64_u32 v[40:41], s[22:23], v66, s51, v[16:17]
	v_mad_u64_u32 v[42:43], s[22:23], v69, s51, v[16:17]
	v_mad_u64_u32 v[44:45], s[22:23], v68, s51, v[16:17]
	v_mad_u64_u32 v[46:47], s[22:23], v71, s51, v[16:17]
	v_mad_u64_u32 v[48:49], s[22:23], v70, s51, v[16:17]
	v_mad_u64_u32 v[50:51], s[22:23], v73, s51, v[16:17]
	v_mad_u64_u32 v[52:53], s[22:23], v72, s51, v[16:17]
	v_mad_u64_u32 v[54:55], s[22:23], v75, s51, v[16:17]
	v_mad_u64_u32 v[56:57], s[22:23], v74, s51, v[16:17]
	v_mad_u64_u32 v[58:59], s[22:23], v77, s51, v[16:17]
	v_mad_u64_u32 v[60:61], s[22:23], v76, s51, v[16:17]
	v_mad_u64_u32 v[62:63], s[22:23], v79, s51, v[16:17]
	v_mad_u64_u32 v[64:65], s[22:23], v78, s51, v[16:17]
	s_waitcnt vmcnt(15)
	ds_write_b32 v34, v80
	s_waitcnt vmcnt(14)
	ds_write_b32 v36, v81
	s_waitcnt vmcnt(13)
	ds_write_b32 v38, v82
	s_waitcnt vmcnt(12)
	ds_write_b32 v40, v83
	s_waitcnt vmcnt(11)
	ds_write_b32 v42, v84
	s_waitcnt vmcnt(10)
	ds_write_b32 v44, v85
	s_waitcnt vmcnt(9)
	ds_write_b32 v46, v86
	s_waitcnt vmcnt(8)
	ds_write_b32 v48, v87
	s_waitcnt vmcnt(7)
	ds_write_b32 v50, v88
	s_waitcnt vmcnt(6)
	ds_write_b32 v52, v89
	s_waitcnt vmcnt(5)
	ds_write_b32 v54, v90
	s_waitcnt vmcnt(4)
	ds_write_b32 v56, v91
	s_waitcnt vmcnt(3)
	ds_write_b32 v58, v92
	s_waitcnt vmcnt(2)
	ds_write_b32 v60, v93
	s_waitcnt vmcnt(1)
	ds_write_b32 v62, v94
	s_waitcnt vmcnt(0)
	ds_write_b32 v64, v95
	s_cbranch_scc1 .LBB0_16
	s_waitcnt lgkmcnt(0)
	ds_read2_b32 v[176:177], v7 offset1:33
	ds_read2_b32 v[178:179], v7 offset0:66 offset1:99
	ds_read2_b32 v[180:181], v7 offset0:132 offset1:165
	ds_read2_b32 v[182:183], v7 offset0:198 offset1:231
	ds_read2_b32 v[184:185], v7 offset0:8 offset1:41
	ds_read2_b32 v[186:187], v7 offset0:74 offset1:107
	ds_read2_b32 v[188:189], v7 offset0:140 offset1:173
	ds_read2_b32 v[190:191], v7 offset0:206 offset1:239
	ds_read2_b32 v[192:193], v7 offset0:16 offset1:49
	ds_read2_b32 v[194:195], v7 offset0:82 offset1:115
	ds_read2_b32 v[196:197], v7 offset0:148 offset1:181
	ds_read2_b32 v[198:199], v7 offset0:214 offset1:247
	ds_read2_b32 v[200:201], v7 offset0:24 offset1:57
	ds_read2_b32 v[202:203], v7 offset0:90 offset1:123
	ds_read2_b32 v[204:205], v7 offset0:156 offset1:189
	ds_read2_b32 v[206:207], v7 offset0:222 offset1:255
	s_waitcnt lgkmcnt(15)
	v_cvt_pk_bf16_f32 v34, v176, v177
	s_waitcnt lgkmcnt(14)
	v_cvt_pk_bf16_f32 v35, v178, v179
	s_mov_b32 s9, s97
	v_or_b32_e32 v0, s18, v5
	s_waitcnt lgkmcnt(13)
	v_cvt_pk_bf16_f32 v36, v180, v181
	v_lshl_add_u64 v[38:39], s[8:9], 1, v[8:9]
	v_lshlrev_b32_e32 v0, 11, v0
	s_waitcnt lgkmcnt(12)
	v_cvt_pk_bf16_f32 v37, v182, v183
	v_lshl_add_u64 v[40:41], v[38:39], 0, v[0:1]
	global_store_dwordx4 v[40:41], v[34:37], off
	v_or_b32_e32 v0, s18, v17
	v_lshlrev_b32_e32 v0, 11, v0
	s_waitcnt lgkmcnt(11)
	v_cvt_pk_bf16_f32 v34, v184, v185
	s_waitcnt lgkmcnt(10)
	v_cvt_pk_bf16_f32 v35, v186, v187
	s_waitcnt lgkmcnt(9)
	v_cvt_pk_bf16_f32 v36, v188, v189
	s_waitcnt lgkmcnt(8)
	v_cvt_pk_bf16_f32 v37, v190, v191
	v_lshl_add_u64 v[40:41], v[38:39], 0, v[0:1]
	global_store_dwordx4 v[40:41], v[34:37], off
	v_or_b32_e32 v0, s18, v31
	v_lshlrev_b32_e32 v0, 11, v0
	s_waitcnt lgkmcnt(7)
	v_cvt_pk_bf16_f32 v34, v192, v193
	s_waitcnt lgkmcnt(6)
	v_cvt_pk_bf16_f32 v35, v194, v195
	s_waitcnt lgkmcnt(5)
	v_cvt_pk_bf16_f32 v36, v196, v197
	s_waitcnt lgkmcnt(4)
	v_cvt_pk_bf16_f32 v37, v198, v199
	v_lshl_add_u64 v[40:41], v[38:39], 0, v[0:1]
	global_store_dwordx4 v[40:41], v[34:37], off
	v_or_b32_e32 v0, s18, v32
	v_lshlrev_b32_e32 v0, 11, v0
	s_waitcnt lgkmcnt(3)
	v_cvt_pk_bf16_f32 v34, v200, v201
	s_waitcnt lgkmcnt(2)
	v_cvt_pk_bf16_f32 v35, v202, v203
	s_waitcnt lgkmcnt(1)
	v_cvt_pk_bf16_f32 v36, v204, v205
	s_waitcnt lgkmcnt(0)
	v_cvt_pk_bf16_f32 v37, v206, v207
	v_lshl_add_u64 v[28:29], v[38:39], 0, v[0:1]
	global_store_dwordx4 v[28:29], v[34:37], off
	s_waitcnt lgkmcnt(0)
	s_mov_b64 s[8:9], 0

.LBB0_20:
	s_lshl_b32 s23, s20, 1
	s_lshl_b32 s22, s18, 1
	v_or_b32_e32 v56, s23, v2
	s_add_i32 s25, s23, 4
	s_add_i32 s24, s22, 4
	s_add_i32 s26, s22, 8
	s_add_i32 s27, s23, 8
	v_add_u32_e32 v0, s8, v56
	v_or_b32_e32 v58, s25, v2
	v_or_b32_e32 v33, s22, v3
	s_add_i32 s28, s22, 12
	s_add_i32 s29, s23, 12
	s_add_i32 s30, s22, 16
	s_add_i32 s34, s22, 20
	s_add_i32 s36, s22, 24
	s_add_i32 s22, s22, 28
	v_or_b32_e32 v57, s24, v3
	v_or_b32_e32 v59, s26, v3
	v_or_b32_e32 v60, s27, v2
	v_lshlrev_b64 v[50:51], 13, v[0:1]
	v_add_u32_e32 v0, s8, v58
	v_mov_b32_e32 v35, v1
	v_mov_b32_e32 v37, v1
	v_mov_b32_e32 v39, v1
	s_add_i32 s31, s23, 16
	v_add_u32_e32 v34, s19, v33
	v_or_b32_e32 v61, s28, v3
	v_or_b32_e32 v62, s29, v2
	v_or_b32_e32 v63, s30, v3
	v_or_b32_e32 v65, s34, v3
	v_or_b32_e32 v67, s36, v3
	v_or_b32_e32 v69, s22, v3
	v_add_u32_e32 v36, s19, v57
	v_add_u32_e32 v38, s19, v59
	v_lshlrev_b64 v[52:53], 13, v[0:1]
	v_add_u32_e32 v0, s8, v60
	v_mov_b32_e32 v41, v1
	v_mov_b32_e32 v43, v1
	v_mov_b32_e32 v45, v1
	v_mov_b32_e32 v47, v1
	v_mov_b32_e32 v49, v1
	s_add_i32 s35, s23, 20
	v_or_b32_e32 v64, s31, v2
	v_lshlrev_b64 v[34:35], 13, v[34:35]
	v_add_u32_e32 v40, s19, v61
	v_add_u32_e32 v42, s19, v63
	v_add_u32_e32 v44, s19, v65
	v_add_u32_e32 v46, s19, v67
	v_add_u32_e32 v48, s19, v69
	v_lshl_add_u64 v[50:51], v[28:29], 0, v[50:51]
	v_lshlrev_b64 v[36:37], 13, v[36:37]
	v_lshlrev_b64 v[38:39], 13, v[38:39]
	v_lshlrev_b64 v[54:55], 13, v[0:1]
	v_add_u32_e32 v0, s8, v62
	s_add_i32 s37, s23, 24
	v_or_b32_e32 v66, s35, v2
	v_lshl_add_u64 v[34:35], v[28:29], 0, v[34:35]
	v_lshlrev_b64 v[40:41], 13, v[40:41]
	v_lshlrev_b64 v[42:43], 13, v[42:43]
	v_lshlrev_b64 v[44:45], 13, v[44:45]
	v_lshlrev_b64 v[46:47], 13, v[46:47]
	v_lshlrev_b64 v[48:49], 13, v[48:49]
	v_lshl_add_u64 v[52:53], v[28:29], 0, v[52:53]
	v_lshl_add_u64 v[36:37], v[28:29], 0, v[36:37]
	v_lshl_add_u64 v[38:39], v[28:29], 0, v[38:39]
	global_load_dword v71, v[50:51], off
	global_load_dword v72, v[34:35], off
	v_lshlrev_b64 v[50:51], 13, v[0:1]
	v_add_u32_e32 v0, s8, v64
	s_add_i32 s23, s23, 28
	v_or_b32_e32 v68, s37, v2
	v_lshl_add_u64 v[40:41], v[28:29], 0, v[40:41]
	v_lshl_add_u64 v[42:43], v[28:29], 0, v[42:43]
	v_lshl_add_u64 v[44:45], v[28:29], 0, v[44:45]
	v_lshl_add_u64 v[46:47], v[28:29], 0, v[46:47]
	v_lshl_add_u64 v[48:49], v[28:29], 0, v[48:49]
	global_load_dword v73, v[52:53], off
	global_load_dword v74, v[36:37], off
	global_load_dword v75, v[38:39], off
	global_load_dword v76, v[40:41], off
	global_load_dword v77, v[42:43], off
	global_load_dword v78, v[44:45], off
	global_load_dword v79, v[46:47], off
	global_load_dword v80, v[48:49], off
	v_lshl_add_u64 v[36:37], v[28:29], 0, v[50:51]
	v_lshlrev_b64 v[38:39], 13, v[0:1]
	v_add_u32_e32 v0, s8, v66
	v_or_b32_e32 v70, s23, v2
	v_lshl_add_u64 v[34:35], v[28:29], 0, v[54:55]
	global_load_dword v81, v[36:37], off
	global_load_dword v82, v[34:35], off
	v_lshlrev_b64 v[36:37], 13, v[0:1]
	v_add_u32_e32 v0, s8, v68
	v_lshl_add_u64 v[34:35], v[28:29], 0, v[38:39]
	v_lshlrev_b64 v[38:39], 13, v[0:1]
	v_add_u32_e32 v0, s8, v70
	v_lshlrev_b64 v[40:41], 13, v[0:1]
	v_lshl_add_u64 v[40:41], v[28:29], 0, v[40:41]
	v_lshl_add_u64 v[36:37], v[28:29], 0, v[36:37]
	v_lshl_add_u64 v[38:39], v[28:29], 0, v[38:39]
	global_load_dword v0, v[40:41], off
	global_load_dword v83, v[38:39], off
	global_load_dword v84, v[36:37], off
	global_load_dword v85, v[34:35], off
	s_add_i32 s20, s20, 16
	s_add_i32 s18, s18, 16
	s_add_i32 s21, s21, -16
	v_mad_u64_u32 v[34:35], s[22:23], v56, s51, v[16:17]
	s_cmp_lg_u32 s21, 0
	v_mad_u64_u32 v[36:37], s[22:23], v33, s51, v[16:17]
	v_mad_u64_u32 v[38:39], s[22:23], v58, s51, v[16:17]
	v_mad_u64_u32 v[40:41], s[22:23], v57, s51, v[16:17]
	v_mad_u64_u32 v[42:43], s[22:23], v60, s51, v[16:17]
	v_mad_u64_u32 v[44:45], s[22:23], v59, s51, v[16:17]
	v_mad_u64_u32 v[46:47], s[22:23], v62, s51, v[16:17]
	v_mad_u64_u32 v[48:49], s[22:23], v61, s51, v[16:17]
	v_mad_u64_u32 v[50:51], s[22:23], v64, s51, v[16:17]
	v_mad_u64_u32 v[52:53], s[22:23], v63, s51, v[16:17]
	v_mad_u64_u32 v[54:55], s[22:23], v66, s51, v[16:17]
	v_mad_u64_u32 v[56:57], s[22:23], v65, s51, v[16:17]
	v_mad_u64_u32 v[58:59], s[22:23], v68, s51, v[16:17]
	v_mad_u64_u32 v[60:61], s[22:23], v67, s51, v[16:17]
	v_mad_u64_u32 v[62:63], s[22:23], v70, s51, v[16:17]
	v_mad_u64_u32 v[64:65], s[22:23], v69, s51, v[16:17]
	s_waitcnt vmcnt(15)
	ds_write_b32 v34, v71
	s_waitcnt vmcnt(14)
	ds_write_b32 v36, v72
	s_waitcnt vmcnt(13)
	ds_write_b32 v38, v73
	s_waitcnt vmcnt(12)
	ds_write_b32 v40, v74
	s_waitcnt vmcnt(4)
	ds_write_b32 v42, v82
	ds_write_b32 v44, v75
	ds_write_b32 v46, v81
	ds_write_b32 v48, v76
	s_waitcnt vmcnt(0)
	ds_write_b32 v50, v85
	ds_write_b32 v52, v77
	ds_write_b32 v54, v84
	ds_write_b32 v56, v78
	ds_write_b32 v58, v83
	ds_write_b32 v60, v79
	ds_write_b32 v62, v0
	ds_write_b32 v64, v80
	s_cbranch_scc1 .LBB0_20
	s_cmpk_lt_u32 s9, 0x80
	s_mov_b32 s9, 0x2c00000
	s_cselect_b32 s9, s9, 0x2d00000
	s_and_b32 s11, s11, 0x3e0
	s_waitcnt lgkmcnt(0)
	s_add_u32 s9, s94, s9
	ds_read2_b32 v[176:177], v7 offset1:33
	ds_read2_b32 v[178:179], v7 offset0:66 offset1:99
	ds_read2_b32 v[180:181], v7 offset0:132 offset1:165
	ds_read2_b32 v[182:183], v7 offset0:198 offset1:231
	ds_read2_b32 v[184:185], v7 offset0:8 offset1:41
	ds_read2_b32 v[186:187], v7 offset0:74 offset1:107
	ds_read2_b32 v[188:189], v7 offset0:140 offset1:173
	ds_read2_b32 v[190:191], v7 offset0:206 offset1:239
	ds_read2_b32 v[192:193], v7 offset0:16 offset1:49
	ds_read2_b32 v[194:195], v7 offset0:82 offset1:115
	ds_read2_b32 v[196:197], v7 offset0:148 offset1:181
	ds_read2_b32 v[198:199], v7 offset0:214 offset1:247
	ds_read2_b32 v[200:201], v7 offset0:24 offset1:57
	ds_read2_b32 v[202:203], v7 offset0:90 offset1:123
	ds_read2_b32 v[204:205], v7 offset0:156 offset1:189
	ds_read2_b32 v[206:207], v7 offset0:222 offset1:255
	s_addc_u32 s18, s95, 0
	s_lshl_b32 s8, s8, 1
	s_waitcnt lgkmcnt(15)
	v_cvt_pk_bf16_f32 v34, v176, v177
	s_add_u32 s8, s9, s8
	v_lshlrev_b32_e32 v0, 1, v6
	s_waitcnt lgkmcnt(14)
	v_cvt_pk_bf16_f32 v35, v178, v179
	v_or_b32_e32 v33, s11, v5
	s_addc_u32 s9, s18, 0
	s_waitcnt lgkmcnt(13)
	v_cvt_pk_bf16_f32 v36, v180, v181
	v_lshl_add_u64 v[38:39], s[8:9], 0, v[0:1]
	v_lshlrev_b32_e32 v0, 9, v33
	s_waitcnt lgkmcnt(12)
	v_cvt_pk_bf16_f32 v37, v182, v183
	v_lshl_add_u64 v[40:41], v[38:39], 0, v[0:1]
	global_store_dwordx4 v[40:41], v[34:37], off
	v_or_b32_e32 v0, s11, v17
	v_lshlrev_b32_e32 v0, 9, v0
	s_waitcnt lgkmcnt(11)
	v_cvt_pk_bf16_f32 v34, v184, v185
	s_waitcnt lgkmcnt(10)
	v_cvt_pk_bf16_f32 v35, v186, v187
	s_waitcnt lgkmcnt(9)
	v_cvt_pk_bf16_f32 v36, v188, v189
	s_waitcnt lgkmcnt(8)
	v_cvt_pk_bf16_f32 v37, v190, v191
	v_lshl_add_u64 v[40:41], v[38:39], 0, v[0:1]
	global_store_dwordx4 v[40:41], v[34:37], off
	v_or_b32_e32 v0, s11, v31
	v_lshlrev_b32_e32 v0, 9, v0
	s_waitcnt lgkmcnt(7)
	v_cvt_pk_bf16_f32 v34, v192, v193
	s_waitcnt lgkmcnt(6)
	v_cvt_pk_bf16_f32 v35, v194, v195
	s_waitcnt lgkmcnt(5)
	v_cvt_pk_bf16_f32 v36, v196, v197
	s_waitcnt lgkmcnt(4)
	v_cvt_pk_bf16_f32 v37, v198, v199
	v_lshl_add_u64 v[40:41], v[38:39], 0, v[0:1]
	global_store_dwordx4 v[40:41], v[34:37], off
	v_or_b32_e32 v0, s11, v32
	v_lshlrev_b32_e32 v0, 9, v0
	s_waitcnt lgkmcnt(3)
	v_cvt_pk_bf16_f32 v34, v200, v201
	s_waitcnt lgkmcnt(2)
	v_cvt_pk_bf16_f32 v35, v202, v203
	s_waitcnt lgkmcnt(1)
	v_cvt_pk_bf16_f32 v36, v204, v205
	s_waitcnt lgkmcnt(0)
	v_cvt_pk_bf16_f32 v37, v206, v207
	v_lshl_add_u64 v[28:29], v[38:39], 0, v[0:1]
	global_store_dwordx4 v[28:29], v[34:37], off
	s_waitcnt lgkmcnt(0)

.LBB0_25:
	s_lshl_b32 s21, s18, 1
	s_lshl_b32 s22, s19, 1
	v_or_b32_e32 v0, s21, v3
	v_or_b32_e32 v33, s22, v2
	s_add_i32 s23, s21, 4
	s_add_i32 s24, s22, 4
	s_add_i32 s25, s21, 8
	s_add_i32 s26, s22, 8
	s_add_i32 s27, s21, 12
	s_add_i32 s28, s22, 12
	s_add_i32 s29, s21, 16
	s_add_i32 s30, s22, 16
	s_add_i32 s31, s21, 20
	s_add_i32 s34, s22, 20
	s_add_i32 s35, s21, 24
	s_add_i32 s36, s22, 24
	s_add_i32 s21, s21, 28
	s_add_i32 s22, s22, 28
	v_add_u32_e32 v34, s9, v33
	v_or_b32_e32 v66, s23, v3
	v_or_b32_e32 v67, s24, v2
	v_or_b32_e32 v68, s25, v3
	v_or_b32_e32 v69, s26, v2
	v_or_b32_e32 v70, s27, v3
	v_or_b32_e32 v71, s28, v2
	v_or_b32_e32 v72, s29, v3
	v_or_b32_e32 v73, s30, v2
	v_or_b32_e32 v74, s31, v3
	v_or_b32_e32 v75, s34, v2
	v_or_b32_e32 v76, s35, v3
	v_or_b32_e32 v77, s36, v2
	v_or_b32_e32 v78, s21, v3
	v_or_b32_e32 v79, s22, v2
	v_add_u32_e32 v36, s11, v0
	v_mad_u64_u32 v[34:35], s[22:23], v34, s54, v[28:29]
	v_add_u32_e32 v40, s11, v66
	v_add_u32_e32 v38, s9, v67
	v_add_u32_e32 v44, s11, v68
	v_add_u32_e32 v42, s9, v69
	v_add_u32_e32 v48, s11, v70
	v_add_u32_e32 v46, s9, v71
	v_add_u32_e32 v52, s11, v72
	v_add_u32_e32 v50, s9, v73
	v_add_u32_e32 v56, s11, v74
	v_add_u32_e32 v54, s9, v75
	v_add_u32_e32 v60, s11, v76
	v_add_u32_e32 v58, s9, v77
	v_add_u32_e32 v64, s11, v78
	v_add_u32_e32 v62, s9, v79
	v_mad_u64_u32 v[36:37], s[22:23], v36, s54, v[28:29]
	v_mad_u64_u32 v[38:39], s[22:23], v38, s54, v[28:29]
	v_mad_u64_u32 v[40:41], s[22:23], v40, s54, v[28:29]
	v_mad_u64_u32 v[42:43], s[22:23], v42, s54, v[28:29]
	v_mad_u64_u32 v[44:45], s[22:23], v44, s54, v[28:29]
	v_mad_u64_u32 v[46:47], s[22:23], v46, s54, v[28:29]
	v_mad_u64_u32 v[48:49], s[22:23], v48, s54, v[28:29]
	v_mad_u64_u32 v[50:51], s[22:23], v50, s54, v[28:29]
	v_mad_u64_u32 v[52:53], s[22:23], v52, s54, v[28:29]
	v_mad_u64_u32 v[54:55], s[22:23], v54, s54, v[28:29]
	v_mad_u64_u32 v[56:57], s[22:23], v56, s54, v[28:29]
	v_mad_u64_u32 v[58:59], s[22:23], v58, s54, v[28:29]
	v_mad_u64_u32 v[60:61], s[22:23], v60, s54, v[28:29]
	v_mad_u64_u32 v[62:63], s[22:23], v62, s54, v[28:29]
	v_mad_u64_u32 v[64:65], s[22:23], v64, s54, v[28:29]
	global_load_dword v80, v[34:35], off
	global_load_dword v81, v[36:37], off
	global_load_dword v82, v[38:39], off
	global_load_dword v83, v[40:41], off
	global_load_dword v84, v[42:43], off
	global_load_dword v85, v[44:45], off
	global_load_dword v86, v[46:47], off
	global_load_dword v87, v[48:49], off
	global_load_dword v88, v[50:51], off
	global_load_dword v89, v[52:53], off
	global_load_dword v90, v[54:55], off
	global_load_dword v91, v[56:57], off
	global_load_dword v92, v[58:59], off
	global_load_dword v93, v[60:61], off
	global_load_dword v94, v[62:63], off
	global_load_dword v95, v[64:65], off
	s_add_i32 s19, s19, 16
	s_add_i32 s18, s18, 16
	s_add_i32 s20, s20, -16
	v_mad_u64_u32 v[34:35], s[22:23], v33, s51, v[16:17]
	s_cmp_lg_u32 s20, 0
	v_mad_u64_u32 v[36:37], s[22:23], v0, s51, v[16:17]
	v_mad_u64_u32 v[38:39], s[22:23], v67, s51, v[16:17]
	v_mad_u64_u32 v[40:41], s[22:23], v66, s51, v[16:17]
	v_mad_u64_u32 v[42:43], s[22:23], v69, s51, v[16:17]
	v_mad_u64_u32 v[44:45], s[22:23], v68, s51, v[16:17]
	v_mad_u64_u32 v[46:47], s[22:23], v71, s51, v[16:17]
	v_mad_u64_u32 v[48:49], s[22:23], v70, s51, v[16:17]
	v_mad_u64_u32 v[50:51], s[22:23], v73, s51, v[16:17]
	v_mad_u64_u32 v[52:53], s[22:23], v72, s51, v[16:17]
	v_mad_u64_u32 v[54:55], s[22:23], v75, s51, v[16:17]
	v_mad_u64_u32 v[56:57], s[22:23], v74, s51, v[16:17]
	v_mad_u64_u32 v[58:59], s[22:23], v77, s51, v[16:17]
	v_mad_u64_u32 v[60:61], s[22:23], v76, s51, v[16:17]
	v_mad_u64_u32 v[62:63], s[22:23], v79, s51, v[16:17]
	v_mad_u64_u32 v[64:65], s[22:23], v78, s51, v[16:17]
	s_waitcnt vmcnt(15)
	ds_write_b32 v34, v80
	s_waitcnt vmcnt(14)
	ds_write_b32 v36, v81
	s_waitcnt vmcnt(13)
	ds_write_b32 v38, v82
	s_waitcnt vmcnt(12)
	ds_write_b32 v40, v83
	s_waitcnt vmcnt(11)
	ds_write_b32 v42, v84
	s_waitcnt vmcnt(10)
	ds_write_b32 v44, v85
	s_waitcnt vmcnt(9)
	ds_write_b32 v46, v86
	s_waitcnt vmcnt(8)
	ds_write_b32 v48, v87
	s_waitcnt vmcnt(7)
	ds_write_b32 v50, v88
	s_waitcnt vmcnt(6)
	ds_write_b32 v52, v89
	s_waitcnt vmcnt(5)
	ds_write_b32 v54, v90
	s_waitcnt vmcnt(4)
	ds_write_b32 v56, v91
	s_waitcnt vmcnt(3)
	ds_write_b32 v58, v92
	s_waitcnt vmcnt(2)
	ds_write_b32 v60, v93
	s_waitcnt vmcnt(1)
	ds_write_b32 v62, v94
	s_waitcnt vmcnt(0)
	ds_write_b32 v64, v95
	s_cbranch_scc1 .LBB0_25
	s_waitcnt lgkmcnt(0)
	ds_read2_b32 v[176:177], v7 offset1:33
	ds_read2_b32 v[178:179], v7 offset0:66 offset1:99
	ds_read2_b32 v[180:181], v7 offset0:132 offset1:165
	ds_read2_b32 v[182:183], v7 offset0:198 offset1:231
	ds_read2_b32 v[184:185], v7 offset0:8 offset1:41
	ds_read2_b32 v[186:187], v7 offset0:74 offset1:107
	ds_read2_b32 v[188:189], v7 offset0:140 offset1:173
	ds_read2_b32 v[190:191], v7 offset0:206 offset1:239
	ds_read2_b32 v[192:193], v7 offset0:16 offset1:49
	ds_read2_b32 v[194:195], v7 offset0:82 offset1:115
	ds_read2_b32 v[196:197], v7 offset0:148 offset1:181
	ds_read2_b32 v[198:199], v7 offset0:214 offset1:247
	ds_read2_b32 v[200:201], v7 offset0:24 offset1:57
	ds_read2_b32 v[202:203], v7 offset0:90 offset1:123
	ds_read2_b32 v[204:205], v7 offset0:156 offset1:189
	ds_read2_b32 v[206:207], v7 offset0:222 offset1:255
	s_and_b32 s8, 0xffff, s8
	s_waitcnt lgkmcnt(15)
	v_cvt_pk_bf16_f32 v34, v176, v177
	v_or_b32_e32 v0, s8, v5
	s_waitcnt lgkmcnt(14)
	v_cvt_pk_bf16_f32 v35, v178, v179
	s_lshl_b32 s96, s9, 1
	v_mul_u32_u24_e32 v0, 0x180, v0
	s_waitcnt lgkmcnt(13)
	v_cvt_pk_bf16_f32 v36, v180, v181
	v_lshl_add_u64 v[38:39], v[10:11], 0, s[96:97]
	v_lshlrev_b32_e32 v0, 1, v0
	s_waitcnt lgkmcnt(12)
	v_cvt_pk_bf16_f32 v37, v182, v183
	v_lshl_add_u64 v[40:41], v[38:39], 0, v[0:1]
	global_store_dwordx4 v[40:41], v[34:37], off
	v_or_b32_e32 v0, s8, v17
	v_mul_u32_u24_e32 v0, 0x180, v0
	s_waitcnt lgkmcnt(11)
	v_cvt_pk_bf16_f32 v34, v184, v185
	s_waitcnt lgkmcnt(10)
	v_cvt_pk_bf16_f32 v35, v186, v187
	s_waitcnt lgkmcnt(9)
	v_cvt_pk_bf16_f32 v36, v188, v189
	v_lshlrev_b32_e32 v0, 1, v0
	s_waitcnt lgkmcnt(8)
	v_cvt_pk_bf16_f32 v37, v190, v191
	v_lshl_add_u64 v[40:41], v[38:39], 0, v[0:1]
	global_store_dwordx4 v[40:41], v[34:37], off
	v_or_b32_e32 v0, s8, v31
	v_mul_u32_u24_e32 v0, 0x180, v0
	s_waitcnt lgkmcnt(7)
	v_cvt_pk_bf16_f32 v34, v192, v193
	s_waitcnt lgkmcnt(6)
	v_cvt_pk_bf16_f32 v35, v194, v195
	s_waitcnt lgkmcnt(5)
	v_cvt_pk_bf16_f32 v36, v196, v197
	v_lshlrev_b32_e32 v0, 1, v0
	s_waitcnt lgkmcnt(4)
	v_cvt_pk_bf16_f32 v37, v198, v199
	v_lshl_add_u64 v[40:41], v[38:39], 0, v[0:1]
	global_store_dwordx4 v[40:41], v[34:37], off
	v_or_b32_e32 v0, s8, v32
	v_mul_u32_u24_e32 v0, 0x180, v0
	s_waitcnt lgkmcnt(3)
	v_cvt_pk_bf16_f32 v34, v200, v201
	s_waitcnt lgkmcnt(2)
	v_cvt_pk_bf16_f32 v35, v202, v203
	s_waitcnt lgkmcnt(1)
	v_cvt_pk_bf16_f32 v36, v204, v205
	v_lshlrev_b32_e32 v0, 1, v0
	s_waitcnt lgkmcnt(0)
	v_cvt_pk_bf16_f32 v37, v206, v207
	v_lshl_add_u64 v[28:29], v[38:39], 0, v[0:1]
	global_store_dwordx4 v[28:29], v[34:37], off
	s_waitcnt lgkmcnt(0)

.LBB0_30:
	s_lshl_b32 s21, s18, 1
	s_lshl_b32 s22, s19, 1
	v_or_b32_e32 v0, s21, v3
	v_or_b32_e32 v33, s22, v2
	s_add_i32 s23, s21, 4
	s_add_i32 s24, s22, 4
	s_add_i32 s25, s21, 8
	s_add_i32 s26, s22, 8
	s_add_i32 s27, s21, 12
	s_add_i32 s28, s22, 12
	s_add_i32 s29, s21, 16
	s_add_i32 s30, s22, 16
	s_add_i32 s31, s21, 20
	s_add_i32 s34, s22, 20
	s_add_i32 s35, s21, 24
	s_add_i32 s36, s22, 24
	s_add_i32 s21, s21, 28
	s_add_i32 s22, s22, 28
	v_add_u32_e32 v34, s9, v33
	v_or_b32_e32 v66, s23, v3
	v_or_b32_e32 v67, s24, v2
	v_or_b32_e32 v68, s25, v3
	v_or_b32_e32 v69, s26, v2
	v_or_b32_e32 v70, s27, v3
	v_or_b32_e32 v71, s28, v2
	v_or_b32_e32 v72, s29, v3
	v_or_b32_e32 v73, s30, v2
	v_or_b32_e32 v74, s31, v3
	v_or_b32_e32 v75, s34, v2
	v_or_b32_e32 v76, s35, v3
	v_or_b32_e32 v77, s36, v2
	v_or_b32_e32 v78, s21, v3
	v_or_b32_e32 v79, s22, v2
	v_add_u32_e32 v36, s11, v0
	v_mad_u64_u32 v[34:35], s[22:23], v34, s0, v[28:29]
	v_add_u32_e32 v40, s11, v66
	v_add_u32_e32 v38, s9, v67
	v_add_u32_e32 v44, s11, v68
	v_add_u32_e32 v42, s9, v69
	v_add_u32_e32 v48, s11, v70
	v_add_u32_e32 v46, s9, v71
	v_add_u32_e32 v52, s11, v72
	v_add_u32_e32 v50, s9, v73
	v_add_u32_e32 v56, s11, v74
	v_add_u32_e32 v54, s9, v75
	v_add_u32_e32 v60, s11, v76
	v_add_u32_e32 v58, s9, v77
	v_add_u32_e32 v64, s11, v78
	v_add_u32_e32 v62, s9, v79
	v_mad_u64_u32 v[36:37], s[22:23], v36, s0, v[28:29]
	v_mad_u64_u32 v[38:39], s[22:23], v38, s0, v[28:29]
	v_mad_u64_u32 v[40:41], s[22:23], v40, s0, v[28:29]
	v_mad_u64_u32 v[42:43], s[22:23], v42, s0, v[28:29]
	v_mad_u64_u32 v[44:45], s[22:23], v44, s0, v[28:29]
	v_mad_u64_u32 v[46:47], s[22:23], v46, s0, v[28:29]
	v_mad_u64_u32 v[48:49], s[22:23], v48, s0, v[28:29]
	v_mad_u64_u32 v[50:51], s[22:23], v50, s0, v[28:29]
	v_mad_u64_u32 v[52:53], s[22:23], v52, s0, v[28:29]
	v_mad_u64_u32 v[54:55], s[22:23], v54, s0, v[28:29]
	v_mad_u64_u32 v[56:57], s[22:23], v56, s0, v[28:29]
	v_mad_u64_u32 v[58:59], s[22:23], v58, s0, v[28:29]
	v_mad_u64_u32 v[60:61], s[22:23], v60, s0, v[28:29]
	v_mad_u64_u32 v[62:63], s[22:23], v62, s0, v[28:29]
	v_mad_u64_u32 v[64:65], s[22:23], v64, s0, v[28:29]
	global_load_dword v80, v[34:35], off
	global_load_dword v81, v[36:37], off
	global_load_dword v82, v[38:39], off
	global_load_dword v83, v[40:41], off
	global_load_dword v84, v[42:43], off
	global_load_dword v85, v[44:45], off
	global_load_dword v86, v[46:47], off
	global_load_dword v87, v[48:49], off
	global_load_dword v88, v[50:51], off
	global_load_dword v89, v[52:53], off
	global_load_dword v90, v[54:55], off
	global_load_dword v91, v[56:57], off
	global_load_dword v92, v[58:59], off
	global_load_dword v93, v[60:61], off
	global_load_dword v94, v[62:63], off
	global_load_dword v95, v[64:65], off
	s_add_i32 s19, s19, 16
	s_add_i32 s18, s18, 16
	s_add_i32 s20, s20, -16
	v_mad_u64_u32 v[34:35], s[22:23], v33, s51, v[16:17]
	s_cmp_lg_u32 s20, 0
	v_mad_u64_u32 v[36:37], s[22:23], v0, s51, v[16:17]
	v_mad_u64_u32 v[38:39], s[22:23], v67, s51, v[16:17]
	v_mad_u64_u32 v[40:41], s[22:23], v66, s51, v[16:17]
	v_mad_u64_u32 v[42:43], s[22:23], v69, s51, v[16:17]
	v_mad_u64_u32 v[44:45], s[22:23], v68, s51, v[16:17]
	v_mad_u64_u32 v[46:47], s[22:23], v71, s51, v[16:17]
	v_mad_u64_u32 v[48:49], s[22:23], v70, s51, v[16:17]
	v_mad_u64_u32 v[50:51], s[22:23], v73, s51, v[16:17]
	v_mad_u64_u32 v[52:53], s[22:23], v72, s51, v[16:17]
	v_mad_u64_u32 v[54:55], s[22:23], v75, s51, v[16:17]
	v_mad_u64_u32 v[56:57], s[22:23], v74, s51, v[16:17]
	v_mad_u64_u32 v[58:59], s[22:23], v77, s51, v[16:17]
	v_mad_u64_u32 v[60:61], s[22:23], v76, s51, v[16:17]
	v_mad_u64_u32 v[62:63], s[22:23], v79, s51, v[16:17]
	v_mad_u64_u32 v[64:65], s[22:23], v78, s51, v[16:17]
	s_waitcnt vmcnt(15)
	ds_write_b32 v34, v80
	s_waitcnt vmcnt(14)
	ds_write_b32 v36, v81
	s_waitcnt vmcnt(13)
	ds_write_b32 v38, v82
	s_waitcnt vmcnt(12)
	ds_write_b32 v40, v83
	s_waitcnt vmcnt(11)
	ds_write_b32 v42, v84
	s_waitcnt vmcnt(10)
	ds_write_b32 v44, v85
	s_waitcnt vmcnt(9)
	ds_write_b32 v46, v86
	s_waitcnt vmcnt(8)
	ds_write_b32 v48, v87
	s_waitcnt vmcnt(7)
	ds_write_b32 v50, v88
	s_waitcnt vmcnt(6)
	ds_write_b32 v52, v89
	s_waitcnt vmcnt(5)
	ds_write_b32 v54, v90
	s_waitcnt vmcnt(4)
	ds_write_b32 v56, v91
	s_waitcnt vmcnt(3)
	ds_write_b32 v58, v92
	s_waitcnt vmcnt(2)
	ds_write_b32 v60, v93
	s_waitcnt vmcnt(1)
	ds_write_b32 v62, v94
	s_waitcnt vmcnt(0)
	ds_write_b32 v64, v95
	s_cbranch_scc1 .LBB0_30
	s_waitcnt lgkmcnt(0)
	ds_read2_b32 v[176:177], v7 offset1:33
	ds_read2_b32 v[178:179], v7 offset0:66 offset1:99
	ds_read2_b32 v[180:181], v7 offset0:132 offset1:165
	ds_read2_b32 v[182:183], v7 offset0:198 offset1:231
	ds_read2_b32 v[184:185], v7 offset0:8 offset1:41
	ds_read2_b32 v[186:187], v7 offset0:74 offset1:107
	ds_read2_b32 v[188:189], v7 offset0:140 offset1:173
	ds_read2_b32 v[190:191], v7 offset0:206 offset1:239
	ds_read2_b32 v[192:193], v7 offset0:16 offset1:49
	ds_read2_b32 v[194:195], v7 offset0:82 offset1:115
	ds_read2_b32 v[196:197], v7 offset0:148 offset1:181
	ds_read2_b32 v[198:199], v7 offset0:214 offset1:247
	ds_read2_b32 v[200:201], v7 offset0:24 offset1:57
	ds_read2_b32 v[202:203], v7 offset0:90 offset1:123
	ds_read2_b32 v[204:205], v7 offset0:156 offset1:189
	ds_read2_b32 v[206:207], v7 offset0:222 offset1:255
	s_waitcnt lgkmcnt(15)
	v_cvt_pk_bf16_f32 v34, v176, v177
	s_and_b32 s8, 0xffff, s8
	s_waitcnt lgkmcnt(14)
	v_cvt_pk_bf16_f32 v35, v178, v179
	s_lshl_b32 s96, s9, 1
	v_or_b32_e32 v0, s8, v5
	s_waitcnt lgkmcnt(13)
	v_cvt_pk_bf16_f32 v36, v180, v181
	v_lshl_add_u64 v[38:39], v[12:13], 0, s[96:97]
	v_lshlrev_b32_e32 v0, 11, v0
	s_waitcnt lgkmcnt(12)
	v_cvt_pk_bf16_f32 v37, v182, v183
	v_lshl_add_u64 v[40:41], v[38:39], 0, v[0:1]
	global_store_dwordx4 v[40:41], v[34:37], off
	v_or_b32_e32 v0, s8, v17
	v_lshlrev_b32_e32 v0, 11, v0
	s_waitcnt lgkmcnt(11)
	v_cvt_pk_bf16_f32 v34, v184, v185
	s_waitcnt lgkmcnt(10)
	v_cvt_pk_bf16_f32 v35, v186, v187
	s_waitcnt lgkmcnt(9)
	v_cvt_pk_bf16_f32 v36, v188, v189
	s_waitcnt lgkmcnt(8)
	v_cvt_pk_bf16_f32 v37, v190, v191
	v_lshl_add_u64 v[40:41], v[38:39], 0, v[0:1]
	global_store_dwordx4 v[40:41], v[34:37], off
	v_or_b32_e32 v0, s8, v31
	v_lshlrev_b32_e32 v0, 11, v0
	s_waitcnt lgkmcnt(7)
	v_cvt_pk_bf16_f32 v34, v192, v193
	s_waitcnt lgkmcnt(6)
	v_cvt_pk_bf16_f32 v35, v194, v195
	s_waitcnt lgkmcnt(5)
	v_cvt_pk_bf16_f32 v36, v196, v197
	s_waitcnt lgkmcnt(4)
	v_cvt_pk_bf16_f32 v37, v198, v199
	v_lshl_add_u64 v[40:41], v[38:39], 0, v[0:1]
	global_store_dwordx4 v[40:41], v[34:37], off
	v_or_b32_e32 v0, s8, v32
	v_lshlrev_b32_e32 v0, 11, v0
	s_waitcnt lgkmcnt(3)
	v_cvt_pk_bf16_f32 v34, v200, v201
	s_waitcnt lgkmcnt(2)
	v_cvt_pk_bf16_f32 v35, v202, v203
	s_waitcnt lgkmcnt(1)
	v_cvt_pk_bf16_f32 v36, v204, v205
	s_waitcnt lgkmcnt(0)
	v_cvt_pk_bf16_f32 v37, v206, v207
	v_lshl_add_u64 v[28:29], v[38:39], 0, v[0:1]
	global_store_dwordx4 v[28:29], v[34:37], off
	s_waitcnt lgkmcnt(0)

.LBB0_36:
	s_lshl_b32 s22, s19, 1
	s_lshl_b32 s21, s11, 1
	v_or_b32_e32 v56, s22, v2
	s_add_i32 s24, s22, 4
	s_add_i32 s23, s21, 4
	s_add_i32 s25, s21, 8
	s_add_i32 s26, s22, 8
	v_add_u32_e32 v0, s9, v56
	v_or_b32_e32 v58, s24, v2
	v_or_b32_e32 v33, s21, v3
	s_add_i32 s27, s21, 12
	s_add_i32 s28, s22, 12
	s_add_i32 s29, s21, 16
	s_add_i32 s31, s21, 20
	s_add_i32 s35, s21, 24
	s_add_i32 s21, s21, 28
	v_or_b32_e32 v57, s23, v3
	v_or_b32_e32 v59, s25, v3
	v_or_b32_e32 v60, s26, v2
	v_lshlrev_b64 v[50:51], 12, v[0:1]
	v_add_u32_e32 v0, s9, v58
	v_mov_b32_e32 v35, v1
	v_mov_b32_e32 v37, v1
	v_mov_b32_e32 v39, v1
	s_add_i32 s30, s22, 16
	v_add_u32_e32 v34, s18, v33
	v_or_b32_e32 v61, s27, v3
	v_or_b32_e32 v62, s28, v2
	v_or_b32_e32 v63, s29, v3
	v_or_b32_e32 v65, s31, v3
	v_or_b32_e32 v67, s35, v3
	v_or_b32_e32 v69, s21, v3
	v_add_u32_e32 v36, s18, v57
	v_add_u32_e32 v38, s18, v59
	v_lshlrev_b64 v[52:53], 12, v[0:1]
	v_add_u32_e32 v0, s9, v60
	v_mov_b32_e32 v41, v1
	v_mov_b32_e32 v43, v1
	v_mov_b32_e32 v45, v1
	v_mov_b32_e32 v47, v1
	v_mov_b32_e32 v49, v1
	s_add_i32 s34, s22, 20
	v_or_b32_e32 v64, s30, v2
	v_lshlrev_b64 v[34:35], 12, v[34:35]
	v_add_u32_e32 v40, s18, v61
	v_add_u32_e32 v42, s18, v63
	v_add_u32_e32 v44, s18, v65
	v_add_u32_e32 v46, s18, v67
	v_add_u32_e32 v48, s18, v69
	v_lshl_add_u64 v[50:51], v[28:29], 0, v[50:51]
	v_lshlrev_b64 v[36:37], 12, v[36:37]
	v_lshlrev_b64 v[38:39], 12, v[38:39]
	v_lshlrev_b64 v[54:55], 12, v[0:1]
	v_add_u32_e32 v0, s9, v62
	s_add_i32 s36, s22, 24
	v_or_b32_e32 v66, s34, v2
	v_lshl_add_u64 v[34:35], v[28:29], 0, v[34:35]
	v_lshlrev_b64 v[40:41], 12, v[40:41]
	v_lshlrev_b64 v[42:43], 12, v[42:43]
	v_lshlrev_b64 v[44:45], 12, v[44:45]
	v_lshlrev_b64 v[46:47], 12, v[46:47]
	v_lshlrev_b64 v[48:49], 12, v[48:49]
	v_lshl_add_u64 v[52:53], v[28:29], 0, v[52:53]
	v_lshl_add_u64 v[36:37], v[28:29], 0, v[36:37]
	v_lshl_add_u64 v[38:39], v[28:29], 0, v[38:39]
	global_load_dword v71, v[50:51], off
	global_load_dword v72, v[34:35], off
	v_lshlrev_b64 v[50:51], 12, v[0:1]
	v_add_u32_e32 v0, s9, v64
	s_add_i32 s22, s22, 28
	v_or_b32_e32 v68, s36, v2
	v_lshl_add_u64 v[40:41], v[28:29], 0, v[40:41]
	v_lshl_add_u64 v[42:43], v[28:29], 0, v[42:43]
	v_lshl_add_u64 v[44:45], v[28:29], 0, v[44:45]
	v_lshl_add_u64 v[46:47], v[28:29], 0, v[46:47]
	v_lshl_add_u64 v[48:49], v[28:29], 0, v[48:49]
	global_load_dword v73, v[52:53], off
	global_load_dword v74, v[36:37], off
	global_load_dword v75, v[38:39], off
	global_load_dword v76, v[40:41], off
	global_load_dword v77, v[42:43], off
	global_load_dword v78, v[44:45], off
	global_load_dword v79, v[46:47], off
	global_load_dword v80, v[48:49], off
	v_lshl_add_u64 v[36:37], v[28:29], 0, v[50:51]
	v_lshlrev_b64 v[38:39], 12, v[0:1]
	v_add_u32_e32 v0, s9, v66
	v_or_b32_e32 v70, s22, v2
	v_lshl_add_u64 v[34:35], v[28:29], 0, v[54:55]
	global_load_dword v81, v[36:37], off
	global_load_dword v82, v[34:35], off
	v_lshlrev_b64 v[36:37], 12, v[0:1]
	v_add_u32_e32 v0, s9, v68
	v_lshl_add_u64 v[34:35], v[28:29], 0, v[38:39]
	v_lshlrev_b64 v[38:39], 12, v[0:1]
	v_add_u32_e32 v0, s9, v70
	v_lshlrev_b64 v[40:41], 12, v[0:1]
	v_lshl_add_u64 v[40:41], v[28:29], 0, v[40:41]
	v_lshl_add_u64 v[36:37], v[28:29], 0, v[36:37]
	v_lshl_add_u64 v[38:39], v[28:29], 0, v[38:39]
	global_load_dword v0, v[40:41], off
	global_load_dword v83, v[38:39], off
	global_load_dword v84, v[36:37], off
	global_load_dword v85, v[34:35], off
	s_add_i32 s19, s19, 16
	s_add_i32 s11, s11, 16
	s_add_i32 s20, s20, -16
	v_mad_u64_u32 v[34:35], s[22:23], v56, s51, v[16:17]
	s_cmp_lg_u32 s20, 0
	v_mad_u64_u32 v[36:37], s[22:23], v33, s51, v[16:17]
	v_mad_u64_u32 v[38:39], s[22:23], v58, s51, v[16:17]
	v_mad_u64_u32 v[40:41], s[22:23], v57, s51, v[16:17]
	v_mad_u64_u32 v[42:43], s[22:23], v60, s51, v[16:17]
	v_mad_u64_u32 v[44:45], s[22:23], v59, s51, v[16:17]
	v_mad_u64_u32 v[46:47], s[22:23], v62, s51, v[16:17]
	v_mad_u64_u32 v[48:49], s[22:23], v61, s51, v[16:17]
	v_mad_u64_u32 v[50:51], s[22:23], v64, s51, v[16:17]
	v_mad_u64_u32 v[52:53], s[22:23], v63, s51, v[16:17]
	v_mad_u64_u32 v[54:55], s[22:23], v66, s51, v[16:17]
	v_mad_u64_u32 v[56:57], s[22:23], v65, s51, v[16:17]
	v_mad_u64_u32 v[58:59], s[22:23], v68, s51, v[16:17]
	v_mad_u64_u32 v[60:61], s[22:23], v67, s51, v[16:17]
	v_mad_u64_u32 v[62:63], s[22:23], v70, s51, v[16:17]
	v_mad_u64_u32 v[64:65], s[22:23], v69, s51, v[16:17]
	s_waitcnt vmcnt(15)
	ds_write_b32 v34, v71
	s_waitcnt vmcnt(14)
	ds_write_b32 v36, v72
	s_waitcnt vmcnt(13)
	ds_write_b32 v38, v73
	s_waitcnt vmcnt(12)
	ds_write_b32 v40, v74
	s_waitcnt vmcnt(4)
	ds_write_b32 v42, v82
	ds_write_b32 v44, v75
	ds_write_b32 v46, v81
	ds_write_b32 v48, v76
	s_waitcnt vmcnt(0)
	ds_write_b32 v50, v85
	ds_write_b32 v52, v77
	ds_write_b32 v54, v84
	ds_write_b32 v56, v78
	ds_write_b32 v58, v83
	ds_write_b32 v60, v79
	ds_write_b32 v62, v0
	ds_write_b32 v64, v80
	s_cbranch_scc1 .LBB0_36
	s_waitcnt lgkmcnt(0)
	ds_read2_b32 v[176:177], v7 offset1:33
	ds_read2_b32 v[178:179], v7 offset0:66 offset1:99
	ds_read2_b32 v[180:181], v7 offset0:132 offset1:165
	ds_read2_b32 v[182:183], v7 offset0:198 offset1:231
	ds_read2_b32 v[184:185], v7 offset0:8 offset1:41
	ds_read2_b32 v[186:187], v7 offset0:74 offset1:107
	ds_read2_b32 v[188:189], v7 offset0:140 offset1:173
	ds_read2_b32 v[190:191], v7 offset0:206 offset1:239
	ds_read2_b32 v[192:193], v7 offset0:16 offset1:49
	ds_read2_b32 v[194:195], v7 offset0:82 offset1:115
	ds_read2_b32 v[196:197], v7 offset0:148 offset1:181
	ds_read2_b32 v[198:199], v7 offset0:214 offset1:247
	ds_read2_b32 v[200:201], v7 offset0:24 offset1:57
	ds_read2_b32 v[202:203], v7 offset0:90 offset1:123
	ds_read2_b32 v[204:205], v7 offset0:156 offset1:189
	ds_read2_b32 v[206:207], v7 offset0:222 offset1:255
	s_waitcnt lgkmcnt(15)
	v_cvt_pk_bf16_f32 v34, v176, v177
	s_waitcnt lgkmcnt(14)
	v_cvt_pk_bf16_f32 v35, v178, v179
	s_lshl_b32 s96, s9, 1
	v_or_b32_e32 v0, s8, v5
	s_waitcnt lgkmcnt(13)
	v_cvt_pk_bf16_f32 v36, v180, v181
	v_lshl_add_u64 v[38:39], v[8:9], 0, s[96:97]
	v_lshlrev_b32_e32 v0, 11, v0
	s_waitcnt lgkmcnt(12)
	v_cvt_pk_bf16_f32 v37, v182, v183
	v_lshl_add_u64 v[40:41], v[38:39], 0, v[0:1]
	global_store_dwordx4 v[40:41], v[34:37], off
	v_or_b32_e32 v0, s8, v17
	v_lshlrev_b32_e32 v0, 11, v0
	s_waitcnt lgkmcnt(11)
	v_cvt_pk_bf16_f32 v34, v184, v185
	s_waitcnt lgkmcnt(10)
	v_cvt_pk_bf16_f32 v35, v186, v187
	s_waitcnt lgkmcnt(9)
	v_cvt_pk_bf16_f32 v36, v188, v189
	s_waitcnt lgkmcnt(8)
	v_cvt_pk_bf16_f32 v37, v190, v191
	v_lshl_add_u64 v[40:41], v[38:39], 0, v[0:1]
	global_store_dwordx4 v[40:41], v[34:37], off
	v_or_b32_e32 v0, s8, v31
	v_lshlrev_b32_e32 v0, 11, v0
	s_waitcnt lgkmcnt(7)
	v_cvt_pk_bf16_f32 v34, v192, v193
	s_waitcnt lgkmcnt(6)
	v_cvt_pk_bf16_f32 v35, v194, v195
	s_waitcnt lgkmcnt(5)
	v_cvt_pk_bf16_f32 v36, v196, v197
	s_waitcnt lgkmcnt(4)
	v_cvt_pk_bf16_f32 v37, v198, v199
	v_lshl_add_u64 v[40:41], v[38:39], 0, v[0:1]
	global_store_dwordx4 v[40:41], v[34:37], off
	v_or_b32_e32 v0, s8, v32
	v_lshlrev_b32_e32 v0, 11, v0
	s_waitcnt lgkmcnt(3)
	v_cvt_pk_bf16_f32 v34, v200, v201
	s_waitcnt lgkmcnt(2)
	v_cvt_pk_bf16_f32 v35, v202, v203
	s_waitcnt lgkmcnt(1)
	v_cvt_pk_bf16_f32 v36, v204, v205
	s_waitcnt lgkmcnt(0)
	v_cvt_pk_bf16_f32 v37, v206, v207
	v_lshl_add_u64 v[28:29], v[38:39], 0, v[0:1]
	global_store_dwordx4 v[28:29], v[34:37], off
	s_waitcnt lgkmcnt(0)
	s_mov_b64 s[8:9], 0

.LBB0_40:
	s_lshl_b32 s20, s11, 1
	s_lshl_b32 s21, s18, 1
	v_or_b32_e32 v0, s20, v3
	v_or_b32_e32 v33, s21, v2
	s_add_i32 s22, s20, 4
	s_add_i32 s23, s21, 4
	s_add_i32 s24, s20, 8
	s_add_i32 s25, s21, 8
	s_add_i32 s26, s20, 12
	s_add_i32 s27, s21, 12
	s_add_i32 s28, s20, 16
	s_add_i32 s29, s21, 16
	s_add_i32 s30, s20, 20
	s_add_i32 s31, s21, 20
	s_add_i32 s34, s20, 24
	s_add_i32 s35, s21, 24
	s_add_i32 s20, s20, 28
	s_add_i32 s21, s21, 28
	v_add_u32_e32 v34, s9, v33
	v_or_b32_e32 v66, s22, v3
	v_or_b32_e32 v67, s23, v2
	v_or_b32_e32 v68, s24, v3
	v_or_b32_e32 v69, s25, v2
	v_or_b32_e32 v70, s26, v3
	v_or_b32_e32 v71, s27, v2
	v_or_b32_e32 v72, s28, v3
	v_or_b32_e32 v73, s29, v2
	v_or_b32_e32 v74, s30, v3
	v_or_b32_e32 v75, s31, v2
	v_or_b32_e32 v76, s34, v3
	v_or_b32_e32 v77, s35, v2
	v_or_b32_e32 v78, s20, v3
	v_or_b32_e32 v79, s21, v2
	v_add_u32_e32 v36, s10, v0
	v_mad_u64_u32 v[34:35], s[20:21], v34, s1, v[28:29]
	v_add_u32_e32 v40, s10, v66
	v_add_u32_e32 v38, s9, v67
	v_add_u32_e32 v44, s10, v68
	v_add_u32_e32 v42, s9, v69
	v_add_u32_e32 v48, s10, v70
	v_add_u32_e32 v46, s9, v71
	v_add_u32_e32 v52, s10, v72
	v_add_u32_e32 v50, s9, v73
	v_add_u32_e32 v56, s10, v74
	v_add_u32_e32 v54, s9, v75
	v_add_u32_e32 v60, s10, v76
	v_add_u32_e32 v58, s9, v77
	v_add_u32_e32 v64, s10, v78
	v_add_u32_e32 v62, s9, v79
	v_mad_u64_u32 v[36:37], s[20:21], v36, s1, v[28:29]
	v_mad_u64_u32 v[38:39], s[20:21], v38, s1, v[28:29]
	v_mad_u64_u32 v[40:41], s[20:21], v40, s1, v[28:29]
	v_mad_u64_u32 v[42:43], s[20:21], v42, s1, v[28:29]
	v_mad_u64_u32 v[44:45], s[20:21], v44, s1, v[28:29]
	v_mad_u64_u32 v[46:47], s[20:21], v46, s1, v[28:29]
	v_mad_u64_u32 v[48:49], s[20:21], v48, s1, v[28:29]
	v_mad_u64_u32 v[50:51], s[20:21], v50, s1, v[28:29]
	v_mad_u64_u32 v[52:53], s[20:21], v52, s1, v[28:29]
	v_mad_u64_u32 v[54:55], s[20:21], v54, s1, v[28:29]
	v_mad_u64_u32 v[56:57], s[20:21], v56, s1, v[28:29]
	v_mad_u64_u32 v[58:59], s[20:21], v58, s1, v[28:29]
	v_mad_u64_u32 v[60:61], s[20:21], v60, s1, v[28:29]
	v_mad_u64_u32 v[62:63], s[20:21], v62, s1, v[28:29]
	v_mad_u64_u32 v[64:65], s[20:21], v64, s1, v[28:29]
	global_load_dword v80, v[34:35], off
	global_load_dword v81, v[36:37], off
	global_load_dword v82, v[38:39], off
	global_load_dword v83, v[40:41], off
	global_load_dword v84, v[42:43], off
	global_load_dword v85, v[44:45], off
	global_load_dword v86, v[46:47], off
	global_load_dword v87, v[48:49], off
	global_load_dword v88, v[50:51], off
	global_load_dword v89, v[52:53], off
	global_load_dword v90, v[54:55], off
	global_load_dword v91, v[56:57], off
	global_load_dword v92, v[58:59], off
	global_load_dword v93, v[60:61], off
	global_load_dword v94, v[62:63], off
	global_load_dword v95, v[64:65], off
	s_add_i32 s18, s18, 16
	s_add_i32 s11, s11, 16
	s_add_i32 s19, s19, -16
	v_mad_u64_u32 v[34:35], s[20:21], v33, s51, v[16:17]
	s_cmp_lg_u32 s19, 0
	v_mad_u64_u32 v[36:37], s[20:21], v0, s51, v[16:17]
	v_mad_u64_u32 v[38:39], s[20:21], v67, s51, v[16:17]
	v_mad_u64_u32 v[40:41], s[20:21], v66, s51, v[16:17]
	v_mad_u64_u32 v[42:43], s[20:21], v69, s51, v[16:17]
	v_mad_u64_u32 v[44:45], s[20:21], v68, s51, v[16:17]
	v_mad_u64_u32 v[46:47], s[20:21], v71, s51, v[16:17]
	v_mad_u64_u32 v[48:49], s[20:21], v70, s51, v[16:17]
	v_mad_u64_u32 v[50:51], s[20:21], v73, s51, v[16:17]
	v_mad_u64_u32 v[52:53], s[20:21], v72, s51, v[16:17]
	v_mad_u64_u32 v[54:55], s[20:21], v75, s51, v[16:17]
	v_mad_u64_u32 v[56:57], s[20:21], v74, s51, v[16:17]
	v_mad_u64_u32 v[58:59], s[20:21], v77, s51, v[16:17]
	v_mad_u64_u32 v[60:61], s[20:21], v76, s51, v[16:17]
	v_mad_u64_u32 v[62:63], s[20:21], v79, s51, v[16:17]
	v_mad_u64_u32 v[64:65], s[20:21], v78, s51, v[16:17]
	s_waitcnt vmcnt(15)
	ds_write_b32 v34, v80
	s_waitcnt vmcnt(14)
	ds_write_b32 v36, v81
	s_waitcnt vmcnt(13)
	ds_write_b32 v38, v82
	s_waitcnt vmcnt(12)
	ds_write_b32 v40, v83
	s_waitcnt vmcnt(11)
	ds_write_b32 v42, v84
	s_waitcnt vmcnt(10)
	ds_write_b32 v44, v85
	s_waitcnt vmcnt(9)
	ds_write_b32 v46, v86
	s_waitcnt vmcnt(8)
	ds_write_b32 v48, v87
	s_waitcnt vmcnt(7)
	ds_write_b32 v50, v88
	s_waitcnt vmcnt(6)
	ds_write_b32 v52, v89
	s_waitcnt vmcnt(5)
	ds_write_b32 v54, v90
	s_waitcnt vmcnt(4)
	ds_write_b32 v56, v91
	s_waitcnt vmcnt(3)
	ds_write_b32 v58, v92
	s_waitcnt vmcnt(2)
	ds_write_b32 v60, v93
	s_waitcnt vmcnt(1)
	ds_write_b32 v62, v94
	s_waitcnt vmcnt(0)
	ds_write_b32 v64, v95
	s_cbranch_scc1 .LBB0_40
	s_waitcnt lgkmcnt(0)
	ds_read2_b32 v[176:177], v7 offset1:33
	ds_read2_b32 v[178:179], v7 offset0:66 offset1:99
	ds_read2_b32 v[180:181], v7 offset0:132 offset1:165
	ds_read2_b32 v[182:183], v7 offset0:198 offset1:231
	ds_read2_b32 v[184:185], v7 offset0:8 offset1:41
	ds_read2_b32 v[186:187], v7 offset0:74 offset1:107
	ds_read2_b32 v[188:189], v7 offset0:140 offset1:173
	ds_read2_b32 v[190:191], v7 offset0:206 offset1:239
	ds_read2_b32 v[192:193], v7 offset0:16 offset1:49
	ds_read2_b32 v[194:195], v7 offset0:82 offset1:115
	ds_read2_b32 v[196:197], v7 offset0:148 offset1:181
	ds_read2_b32 v[198:199], v7 offset0:214 offset1:247
	ds_read2_b32 v[200:201], v7 offset0:24 offset1:57
	ds_read2_b32 v[202:203], v7 offset0:90 offset1:123
	ds_read2_b32 v[204:205], v7 offset0:156 offset1:189
	ds_read2_b32 v[206:207], v7 offset0:222 offset1:255
	s_waitcnt lgkmcnt(15)
	v_cvt_pk_bf16_f32 v34, v176, v177
	s_and_b32 s8, 0xffff, s8
	s_and_b32 s9, 0xffff, s9
	s_waitcnt lgkmcnt(14)
	v_cvt_pk_bf16_f32 v35, v178, v179
	s_lshl_b32 s96, s9, 1
	v_or_b32_e32 v0, s8, v5
	s_waitcnt lgkmcnt(13)
	v_cvt_pk_bf16_f32 v36, v180, v181
	v_lshl_add_u64 v[38:39], v[12:13], 0, s[96:97]
	v_lshlrev_b32_e32 v0, 11, v0
	s_waitcnt lgkmcnt(12)
	v_cvt_pk_bf16_f32 v37, v182, v183
	v_lshl_add_u64 v[40:41], v[38:39], 0, v[0:1]
	global_store_dwordx4 v[40:41], v[34:37], off
	v_or_b32_e32 v0, s8, v17
	v_lshlrev_b32_e32 v0, 11, v0
	s_waitcnt lgkmcnt(11)
	v_cvt_pk_bf16_f32 v34, v184, v185
	s_waitcnt lgkmcnt(10)
	v_cvt_pk_bf16_f32 v35, v186, v187
	s_waitcnt lgkmcnt(9)
	v_cvt_pk_bf16_f32 v36, v188, v189
	s_waitcnt lgkmcnt(8)
	v_cvt_pk_bf16_f32 v37, v190, v191
	v_lshl_add_u64 v[40:41], v[38:39], 0, v[0:1]
	global_store_dwordx4 v[40:41], v[34:37], off
	v_or_b32_e32 v0, s8, v31
	v_lshlrev_b32_e32 v0, 11, v0
	s_waitcnt lgkmcnt(7)
	v_cvt_pk_bf16_f32 v34, v192, v193
	s_waitcnt lgkmcnt(6)
	v_cvt_pk_bf16_f32 v35, v194, v195
	s_waitcnt lgkmcnt(5)
	v_cvt_pk_bf16_f32 v36, v196, v197
	s_waitcnt lgkmcnt(4)
	v_cvt_pk_bf16_f32 v37, v198, v199
	v_lshl_add_u64 v[40:41], v[38:39], 0, v[0:1]
	global_store_dwordx4 v[40:41], v[34:37], off
	v_or_b32_e32 v0, s8, v32
	v_lshlrev_b32_e32 v0, 11, v0
	s_waitcnt lgkmcnt(3)
	v_cvt_pk_bf16_f32 v34, v200, v201
	s_waitcnt lgkmcnt(2)
	v_cvt_pk_bf16_f32 v35, v202, v203
	s_waitcnt lgkmcnt(1)
	v_cvt_pk_bf16_f32 v36, v204, v205
	s_waitcnt lgkmcnt(0)
	v_cvt_pk_bf16_f32 v37, v206, v207
	v_lshl_add_u64 v[28:29], v[38:39], 0, v[0:1]
	global_store_dwordx4 v[28:29], v[34:37], off
	s_waitcnt lgkmcnt(0)

.LBB0_46:
	s_lshl_b32 s23, s11, 1
	s_lshl_b32 s24, s21, 1
	v_or_b32_e32 v33, s23, v3
	v_or_b32_e32 v66, s24, v2
	s_add_i32 s25, s23, 4
	s_add_i32 s26, s24, 4
	s_add_i32 s27, s23, 8
	s_add_i32 s28, s24, 8
	s_add_i32 s29, s23, 12
	s_add_i32 s30, s24, 12
	s_add_i32 s31, s23, 16
	s_add_i32 s34, s24, 16
	s_add_i32 s35, s23, 20
	s_add_i32 s36, s24, 20
	s_add_i32 s37, s23, 24
	s_add_i32 s38, s24, 24
	s_add_i32 s23, s23, 28
	s_add_i32 s24, s24, 28
	v_add_u32_e32 v36, s10, v66
	v_or_b32_e32 v67, s25, v3
	v_or_b32_e32 v68, s26, v2
	v_or_b32_e32 v69, s27, v3
	v_or_b32_e32 v70, s28, v2
	v_or_b32_e32 v71, s29, v3
	v_or_b32_e32 v72, s30, v2
	v_or_b32_e32 v73, s31, v3
	v_or_b32_e32 v74, s34, v2
	v_or_b32_e32 v75, s35, v3
	v_or_b32_e32 v76, s36, v2
	v_or_b32_e32 v77, s37, v3
	v_or_b32_e32 v78, s38, v2
	v_or_b32_e32 v79, s23, v3
	v_or_b32_e32 v80, s24, v2
	v_add_u32_e32 v34, s20, v33
	v_ashrrev_i32_e32 v37, 31, v36
	v_add_u32_e32 v38, s20, v67
	v_add_u32_e32 v40, s10, v68
	v_add_u32_e32 v42, s20, v69
	v_add_u32_e32 v44, s10, v70
	v_add_u32_e32 v46, s20, v71
	v_add_u32_e32 v48, s10, v72
	v_add_u32_e32 v50, s20, v73
	v_add_u32_e32 v52, s10, v74
	v_add_u32_e32 v54, s20, v75
	v_add_u32_e32 v56, s10, v76
	v_add_u32_e32 v58, s20, v77
	v_add_u32_e32 v60, s10, v78
	v_add_u32_e32 v62, s20, v79
	v_add_u32_e32 v64, s10, v80
	v_ashrrev_i32_e32 v35, 31, v34
	v_lshlrev_b64 v[36:37], 12, v[36:37]
	v_ashrrev_i32_e32 v41, 31, v40
	v_ashrrev_i32_e32 v39, 31, v38
	v_ashrrev_i32_e32 v45, 31, v44
	v_ashrrev_i32_e32 v43, 31, v42
	v_ashrrev_i32_e32 v49, 31, v48
	v_ashrrev_i32_e32 v47, 31, v46
	v_ashrrev_i32_e32 v53, 31, v52
	v_ashrrev_i32_e32 v51, 31, v50
	v_ashrrev_i32_e32 v57, 31, v56
	v_ashrrev_i32_e32 v55, 31, v54
	v_ashrrev_i32_e32 v61, 31, v60
	v_ashrrev_i32_e32 v59, 31, v58
	v_ashrrev_i32_e32 v65, 31, v64
	v_ashrrev_i32_e32 v63, 31, v62
	v_lshlrev_b64 v[34:35], 12, v[34:35]
	v_lshl_add_u64 v[36:37], v[28:29], 0, v[36:37]
	v_lshlrev_b64 v[38:39], 12, v[38:39]
	v_lshlrev_b64 v[40:41], 12, v[40:41]
	v_lshlrev_b64 v[42:43], 12, v[42:43]
	v_lshlrev_b64 v[44:45], 12, v[44:45]
	v_lshlrev_b64 v[46:47], 12, v[46:47]
	v_lshlrev_b64 v[48:49], 12, v[48:49]
	v_lshlrev_b64 v[50:51], 12, v[50:51]
	v_lshlrev_b64 v[52:53], 12, v[52:53]
	v_lshlrev_b64 v[54:55], 12, v[54:55]
	v_lshlrev_b64 v[56:57], 12, v[56:57]
	v_lshlrev_b64 v[58:59], 12, v[58:59]
	v_lshlrev_b64 v[60:61], 12, v[60:61]
	v_lshlrev_b64 v[62:63], 12, v[62:63]
	v_lshlrev_b64 v[64:65], 12, v[64:65]
	v_lshl_add_u64 v[34:35], v[28:29], 0, v[34:35]
	v_lshl_add_u64 v[40:41], v[28:29], 0, v[40:41]
	v_lshl_add_u64 v[38:39], v[28:29], 0, v[38:39]
	v_lshl_add_u64 v[44:45], v[28:29], 0, v[44:45]
	v_lshl_add_u64 v[42:43], v[28:29], 0, v[42:43]
	v_lshl_add_u64 v[48:49], v[28:29], 0, v[48:49]
	v_lshl_add_u64 v[46:47], v[28:29], 0, v[46:47]
	v_lshl_add_u64 v[52:53], v[28:29], 0, v[52:53]
	v_lshl_add_u64 v[50:51], v[28:29], 0, v[50:51]
	v_lshl_add_u64 v[56:57], v[28:29], 0, v[56:57]
	v_lshl_add_u64 v[54:55], v[28:29], 0, v[54:55]
	v_lshl_add_u64 v[60:61], v[28:29], 0, v[60:61]
	v_lshl_add_u64 v[58:59], v[28:29], 0, v[58:59]
	v_lshl_add_u64 v[64:65], v[28:29], 0, v[64:65]
	v_lshl_add_u64 v[62:63], v[28:29], 0, v[62:63]
	global_load_dword v81, v[36:37], off
	global_load_dword v82, v[34:35], off
	global_load_dword v83, v[40:41], off
	global_load_dword v84, v[38:39], off
	global_load_dword v85, v[44:45], off
	global_load_dword v86, v[42:43], off
	global_load_dword v87, v[48:49], off
	global_load_dword v88, v[46:47], off
	global_load_dword v89, v[52:53], off
	global_load_dword v90, v[50:51], off
	global_load_dword v91, v[56:57], off
	global_load_dword v92, v[54:55], off
	global_load_dword v93, v[60:61], off
	global_load_dword v94, v[58:59], off
	global_load_dword v95, v[64:65], off
	global_load_dword v96, v[62:63], off
	s_add_i32 s21, s21, 16
	s_add_i32 s11, s11, 16
	s_add_i32 s22, s22, -16
	v_mad_u64_u32 v[34:35], s[24:25], v66, s51, v[16:17]
	s_cmp_lg_u32 s22, 0
	v_mad_u64_u32 v[36:37], s[24:25], v33, s51, v[16:17]
	v_mad_u64_u32 v[38:39], s[24:25], v68, s51, v[16:17]
	v_mad_u64_u32 v[40:41], s[24:25], v67, s51, v[16:17]
	v_mad_u64_u32 v[42:43], s[24:25], v70, s51, v[16:17]
	v_mad_u64_u32 v[44:45], s[24:25], v69, s51, v[16:17]
	v_mad_u64_u32 v[46:47], s[24:25], v72, s51, v[16:17]
	v_mad_u64_u32 v[48:49], s[24:25], v71, s51, v[16:17]
	v_mad_u64_u32 v[50:51], s[24:25], v74, s51, v[16:17]
	v_mad_u64_u32 v[52:53], s[24:25], v73, s51, v[16:17]
	v_mad_u64_u32 v[54:55], s[24:25], v76, s51, v[16:17]
	v_mad_u64_u32 v[56:57], s[24:25], v75, s51, v[16:17]
	v_mad_u64_u32 v[58:59], s[24:25], v78, s51, v[16:17]
	v_mad_u64_u32 v[60:61], s[24:25], v77, s51, v[16:17]
	v_mad_u64_u32 v[62:63], s[24:25], v80, s51, v[16:17]
	v_mad_u64_u32 v[64:65], s[24:25], v79, s51, v[16:17]
	s_waitcnt vmcnt(15)
	ds_write_b32 v34, v81
	s_waitcnt vmcnt(14)
	ds_write_b32 v36, v82
	s_waitcnt vmcnt(13)
	ds_write_b32 v38, v83
	s_waitcnt vmcnt(12)
	ds_write_b32 v40, v84
	s_waitcnt vmcnt(11)
	ds_write_b32 v42, v85
	s_waitcnt vmcnt(10)
	ds_write_b32 v44, v86
	s_waitcnt vmcnt(9)
	ds_write_b32 v46, v87
	s_waitcnt vmcnt(8)
	ds_write_b32 v48, v88
	s_waitcnt vmcnt(7)
	ds_write_b32 v50, v89
	s_waitcnt vmcnt(6)
	ds_write_b32 v52, v90
	s_waitcnt vmcnt(5)
	ds_write_b32 v54, v91
	s_waitcnt vmcnt(4)
	ds_write_b32 v56, v92
	s_waitcnt vmcnt(3)
	ds_write_b32 v58, v93
	s_waitcnt vmcnt(2)
	ds_write_b32 v60, v94
	s_waitcnt vmcnt(1)
	ds_write_b32 v62, v95
	s_waitcnt vmcnt(0)
	ds_write_b32 v64, v96
	s_cbranch_scc1 .LBB0_46
	s_add_i32 s11, s17, 0x107f
	s_cmpk_lt_u32 s11, 0x20ff
	s_mov_b32 s11, 0xb00000
	s_cselect_b32 s11, s11, 0x1b80000
	s_add_u32 s20, s94, s11
	s_waitcnt lgkmcnt(0)
	s_addc_u32 s21, s95, 0
	s_ashr_i32 s11, s10, 31
	ds_read2_b32 v[176:177], v7 offset1:33
	ds_read2_b32 v[178:179], v7 offset0:66 offset1:99
	ds_read2_b32 v[180:181], v7 offset0:132 offset1:165
	ds_read2_b32 v[182:183], v7 offset0:198 offset1:231
	ds_read2_b32 v[184:185], v7 offset0:8 offset1:41
	ds_read2_b32 v[186:187], v7 offset0:74 offset1:107
	ds_read2_b32 v[188:189], v7 offset0:140 offset1:173
	ds_read2_b32 v[190:191], v7 offset0:206 offset1:239
	ds_read2_b32 v[192:193], v7 offset0:16 offset1:49
	ds_read2_b32 v[194:195], v7 offset0:82 offset1:115
	ds_read2_b32 v[196:197], v7 offset0:148 offset1:181
	ds_read2_b32 v[198:199], v7 offset0:214 offset1:247
	ds_read2_b32 v[200:201], v7 offset0:24 offset1:57
	ds_read2_b32 v[202:203], v7 offset0:90 offset1:123
	ds_read2_b32 v[204:205], v7 offset0:156 offset1:189
	ds_read2_b32 v[206:207], v7 offset0:222 offset1:255
	s_lshl_b64 s[10:11], s[10:11], 1
	s_waitcnt lgkmcnt(15)
	v_cvt_pk_bf16_f32 v34, v176, v177
	v_or_b32_e32 v33, s19, v5
	s_add_u32 s10, s20, s10
	v_lshlrev_b32_e32 v38, 1, v6
	v_mov_b32_e32 v39, v1
	s_waitcnt lgkmcnt(14)
	v_cvt_pk_bf16_f32 v35, v178, v179
	s_addc_u32 s11, s21, s11
	v_mul_u32_u24_e32 v33, 0xb00, v33
	s_waitcnt lgkmcnt(13)
	v_cvt_pk_bf16_f32 v36, v180, v181
	v_lshl_add_u64 v[38:39], s[10:11], 0, v[38:39]
	v_lshlrev_b32_e32 v40, 1, v33
	v_mov_b32_e32 v41, v1
	s_waitcnt lgkmcnt(12)
	v_cvt_pk_bf16_f32 v37, v182, v183
	v_lshl_add_u64 v[40:41], v[38:39], 0, v[40:41]
	global_store_dwordx4 v[40:41], v[34:37], off
	v_or_b32_e32 v33, s19, v17
	v_mul_u32_u24_e32 v33, 0xb00, v33
	s_waitcnt lgkmcnt(11)
	v_cvt_pk_bf16_f32 v34, v184, v185
	s_waitcnt lgkmcnt(10)
	v_cvt_pk_bf16_f32 v35, v186, v187
	s_waitcnt lgkmcnt(9)
	v_cvt_pk_bf16_f32 v36, v188, v189
	v_mov_b32_e32 v41, v1
	v_lshlrev_b32_e32 v40, 1, v33
	s_waitcnt lgkmcnt(8)
	v_cvt_pk_bf16_f32 v37, v190, v191
	v_lshl_add_u64 v[40:41], v[38:39], 0, v[40:41]
	global_store_dwordx4 v[40:41], v[34:37], off
	v_or_b32_e32 v33, s19, v31
	v_mul_u32_u24_e32 v33, 0xb00, v33
	s_waitcnt lgkmcnt(7)
	v_cvt_pk_bf16_f32 v34, v192, v193
	s_waitcnt lgkmcnt(6)
	v_cvt_pk_bf16_f32 v35, v194, v195
	s_waitcnt lgkmcnt(5)
	v_cvt_pk_bf16_f32 v36, v196, v197
	v_mov_b32_e32 v41, v1
	v_lshlrev_b32_e32 v40, 1, v33
	s_waitcnt lgkmcnt(4)
	v_cvt_pk_bf16_f32 v37, v198, v199
	v_lshl_add_u64 v[40:41], v[38:39], 0, v[40:41]
	global_store_dwordx4 v[40:41], v[34:37], off
	v_or_b32_e32 v33, s19, v32
	v_mul_u32_u24_e32 v33, 0xb00, v33
	s_waitcnt lgkmcnt(3)
	v_cvt_pk_bf16_f32 v34, v200, v201
	s_waitcnt lgkmcnt(2)
	v_cvt_pk_bf16_f32 v35, v202, v203
	s_waitcnt lgkmcnt(1)
	v_cvt_pk_bf16_f32 v36, v204, v205
	v_mov_b32_e32 v41, v1
	v_lshlrev_b32_e32 v40, 1, v33
	s_waitcnt lgkmcnt(0)
	v_cvt_pk_bf16_f32 v37, v206, v207
	v_lshl_add_u64 v[28:29], v[38:39], 0, v[40:41]
	global_store_dwordx4 v[28:29], v[34:37], off
	s_waitcnt lgkmcnt(0)
	s_mov_b64 s[10:11], 0

.LBB0_50:
	s_lshl_b32 s20, s18, 1
	s_lshl_b32 s21, s11, 1
	v_or_b32_e32 v0, s20, v3
	v_or_b32_e32 v33, s21, v2
	s_add_i32 s22, s20, 4
	s_add_i32 s23, s21, 4
	s_add_i32 s24, s20, 8
	s_add_i32 s25, s21, 8
	s_add_i32 s26, s20, 12
	s_add_i32 s27, s21, 12
	s_add_i32 s28, s20, 16
	s_add_i32 s29, s21, 16
	s_add_i32 s30, s20, 20
	s_add_i32 s31, s21, 20
	s_add_i32 s34, s20, 24
	s_add_i32 s35, s21, 24
	s_add_i32 s20, s20, 28
	s_add_i32 s21, s21, 28
	v_add_u32_e32 v34, s8, v33
	v_or_b32_e32 v66, s22, v3
	v_or_b32_e32 v67, s23, v2
	v_or_b32_e32 v68, s24, v3
	v_or_b32_e32 v69, s25, v2
	v_or_b32_e32 v70, s26, v3
	v_or_b32_e32 v71, s27, v2
	v_or_b32_e32 v72, s28, v3
	v_or_b32_e32 v73, s29, v2
	v_or_b32_e32 v74, s30, v3
	v_or_b32_e32 v75, s31, v2
	v_or_b32_e32 v76, s34, v3
	v_or_b32_e32 v77, s35, v2
	v_or_b32_e32 v78, s20, v3
	v_or_b32_e32 v79, s21, v2
	v_add_u32_e32 v36, s9, v0
	v_mad_i64_i32 v[34:35], s[20:21], v34, s88, v[28:29]
	v_add_u32_e32 v40, s9, v66
	v_add_u32_e32 v38, s8, v67
	v_add_u32_e32 v44, s9, v68
	v_add_u32_e32 v42, s8, v69
	v_add_u32_e32 v48, s9, v70
	v_add_u32_e32 v46, s8, v71
	v_add_u32_e32 v52, s9, v72
	v_add_u32_e32 v50, s8, v73
	v_add_u32_e32 v56, s9, v74
	v_add_u32_e32 v54, s8, v75
	v_add_u32_e32 v60, s9, v76
	v_add_u32_e32 v58, s8, v77
	v_add_u32_e32 v64, s9, v78
	v_add_u32_e32 v62, s8, v79
	v_mad_i64_i32 v[36:37], s[20:21], v36, s88, v[28:29]
	v_mad_i64_i32 v[38:39], s[20:21], v38, s88, v[28:29]
	v_mad_i64_i32 v[40:41], s[20:21], v40, s88, v[28:29]
	v_mad_i64_i32 v[42:43], s[20:21], v42, s88, v[28:29]
	v_mad_i64_i32 v[44:45], s[20:21], v44, s88, v[28:29]
	v_mad_i64_i32 v[46:47], s[20:21], v46, s88, v[28:29]
	v_mad_i64_i32 v[48:49], s[20:21], v48, s88, v[28:29]
	v_mad_i64_i32 v[50:51], s[20:21], v50, s88, v[28:29]
	v_mad_i64_i32 v[52:53], s[20:21], v52, s88, v[28:29]
	v_mad_i64_i32 v[54:55], s[20:21], v54, s88, v[28:29]
	v_mad_i64_i32 v[56:57], s[20:21], v56, s88, v[28:29]
	v_mad_i64_i32 v[58:59], s[20:21], v58, s88, v[28:29]
	v_mad_i64_i32 v[60:61], s[20:21], v60, s88, v[28:29]
	v_mad_i64_i32 v[62:63], s[20:21], v62, s88, v[28:29]
	v_mad_i64_i32 v[64:65], s[20:21], v64, s88, v[28:29]
	global_load_dword v80, v[34:35], off
	global_load_dword v81, v[36:37], off
	global_load_dword v82, v[38:39], off
	global_load_dword v83, v[40:41], off
	global_load_dword v84, v[42:43], off
	global_load_dword v85, v[44:45], off
	global_load_dword v86, v[46:47], off
	global_load_dword v87, v[48:49], off
	global_load_dword v88, v[50:51], off
	global_load_dword v89, v[52:53], off
	global_load_dword v90, v[54:55], off
	global_load_dword v91, v[56:57], off
	global_load_dword v92, v[58:59], off
	global_load_dword v93, v[60:61], off
	global_load_dword v94, v[62:63], off
	global_load_dword v95, v[64:65], off
	s_add_i32 s11, s11, 16
	s_add_i32 s18, s18, 16
	s_add_i32 s19, s19, -16
	v_mad_u64_u32 v[34:35], s[20:21], v33, s51, v[16:17]
	s_cmp_lg_u32 s19, 0
	v_mad_u64_u32 v[36:37], s[20:21], v0, s51, v[16:17]
	v_mad_u64_u32 v[38:39], s[20:21], v67, s51, v[16:17]
	v_mad_u64_u32 v[40:41], s[20:21], v66, s51, v[16:17]
	v_mad_u64_u32 v[42:43], s[20:21], v69, s51, v[16:17]
	v_mad_u64_u32 v[44:45], s[20:21], v68, s51, v[16:17]
	v_mad_u64_u32 v[46:47], s[20:21], v71, s51, v[16:17]
	v_mad_u64_u32 v[48:49], s[20:21], v70, s51, v[16:17]
	v_mad_u64_u32 v[50:51], s[20:21], v73, s51, v[16:17]
	v_mad_u64_u32 v[52:53], s[20:21], v72, s51, v[16:17]
	v_mad_u64_u32 v[54:55], s[20:21], v75, s51, v[16:17]
	v_mad_u64_u32 v[56:57], s[20:21], v74, s51, v[16:17]
	v_mad_u64_u32 v[58:59], s[20:21], v77, s51, v[16:17]
	v_mad_u64_u32 v[60:61], s[20:21], v76, s51, v[16:17]
	v_mad_u64_u32 v[62:63], s[20:21], v79, s51, v[16:17]
	v_mad_u64_u32 v[64:65], s[20:21], v78, s51, v[16:17]
	s_waitcnt vmcnt(15)
	ds_write_b32 v34, v80
	s_waitcnt vmcnt(14)
	ds_write_b32 v36, v81
	s_waitcnt vmcnt(13)
	ds_write_b32 v38, v82
	s_waitcnt vmcnt(12)
	ds_write_b32 v40, v83
	s_waitcnt vmcnt(11)
	ds_write_b32 v42, v84
	s_waitcnt vmcnt(10)
	ds_write_b32 v44, v85
	s_waitcnt vmcnt(9)
	ds_write_b32 v46, v86
	s_waitcnt vmcnt(8)
	ds_write_b32 v48, v87
	s_waitcnt vmcnt(7)
	ds_write_b32 v50, v88
	s_waitcnt vmcnt(6)
	ds_write_b32 v52, v89
	s_waitcnt vmcnt(5)
	ds_write_b32 v54, v90
	s_waitcnt vmcnt(4)
	ds_write_b32 v56, v91
	s_waitcnt vmcnt(3)
	ds_write_b32 v58, v92
	s_waitcnt vmcnt(2)
	ds_write_b32 v60, v93
	s_waitcnt vmcnt(1)
	ds_write_b32 v62, v94
	s_waitcnt vmcnt(0)
	ds_write_b32 v64, v95
	s_cbranch_scc1 .LBB0_50
	s_add_i32 s9, s17, 0x107f
	s_cmpk_lt_u32 s9, 0x20ff
	s_cselect_b32 s9, 0, 0x1080000
	s_add_u32 s11, s94, s9
	s_waitcnt lgkmcnt(0)
	s_addc_u32 s18, s95, 0
	s_ashr_i32 s9, s8, 31
	ds_read2_b32 v[176:177], v7 offset1:33
	ds_read2_b32 v[178:179], v7 offset0:66 offset1:99
	ds_read2_b32 v[180:181], v7 offset0:132 offset1:165
	ds_read2_b32 v[182:183], v7 offset0:198 offset1:231
	ds_read2_b32 v[184:185], v7 offset0:8 offset1:41
	ds_read2_b32 v[186:187], v7 offset0:74 offset1:107
	ds_read2_b32 v[188:189], v7 offset0:140 offset1:173
	ds_read2_b32 v[190:191], v7 offset0:206 offset1:239
	ds_read2_b32 v[192:193], v7 offset0:16 offset1:49
	ds_read2_b32 v[194:195], v7 offset0:82 offset1:115
	ds_read2_b32 v[196:197], v7 offset0:148 offset1:181
	ds_read2_b32 v[198:199], v7 offset0:214 offset1:247
	ds_read2_b32 v[200:201], v7 offset0:24 offset1:57
	ds_read2_b32 v[202:203], v7 offset0:90 offset1:123
	ds_read2_b32 v[204:205], v7 offset0:156 offset1:189
	ds_read2_b32 v[206:207], v7 offset0:222 offset1:255
	s_lshl_b64 s[8:9], s[8:9], 1
	s_waitcnt lgkmcnt(15)
	v_cvt_pk_bf16_f32 v34, v176, v177
	v_or_b32_e32 v36, s10, v5
	s_add_u32 s8, s11, s8
	v_lshlrev_b32_e32 v0, 1, v6
	s_waitcnt lgkmcnt(14)
	v_cvt_pk_bf16_f32 v35, v178, v179
	v_ashrrev_i32_e32 v37, 31, v36
	s_addc_u32 s9, s18, s9
	v_lshlrev_b64 v[38:39], 11, v[36:37]
	s_waitcnt lgkmcnt(13)
	v_cvt_pk_bf16_f32 v36, v180, v181
	v_lshl_add_u64 v[40:41], s[8:9], 0, v[0:1]
	s_waitcnt lgkmcnt(12)
	v_cvt_pk_bf16_f32 v37, v182, v183
	v_lshl_add_u64 v[38:39], v[40:41], 0, v[38:39]
	global_store_dwordx4 v[38:39], v[34:37], off
	v_or_b32_e32 v38, s10, v17
	v_ashrrev_i32_e32 v39, 31, v38
	s_waitcnt lgkmcnt(11)
	v_cvt_pk_bf16_f32 v34, v184, v185
	s_waitcnt lgkmcnt(10)
	v_cvt_pk_bf16_f32 v35, v186, v187
	s_waitcnt lgkmcnt(9)
	v_cvt_pk_bf16_f32 v36, v188, v189
	v_lshlrev_b64 v[38:39], 11, v[38:39]
	s_waitcnt lgkmcnt(8)
	v_cvt_pk_bf16_f32 v37, v190, v191
	v_lshl_add_u64 v[38:39], v[40:41], 0, v[38:39]
	global_store_dwordx4 v[38:39], v[34:37], off
	v_or_b32_e32 v38, s10, v31
	v_ashrrev_i32_e32 v39, 31, v38
	s_waitcnt lgkmcnt(7)
	v_cvt_pk_bf16_f32 v34, v192, v193
	s_waitcnt lgkmcnt(6)
	v_cvt_pk_bf16_f32 v35, v194, v195
	s_waitcnt lgkmcnt(5)
	v_cvt_pk_bf16_f32 v36, v196, v197
	v_lshlrev_b64 v[38:39], 11, v[38:39]
	s_waitcnt lgkmcnt(4)
	v_cvt_pk_bf16_f32 v37, v198, v199
	v_lshl_add_u64 v[38:39], v[40:41], 0, v[38:39]
	global_store_dwordx4 v[38:39], v[34:37], off
	v_or_b32_e32 v38, s10, v32
	v_ashrrev_i32_e32 v39, 31, v38
	s_waitcnt lgkmcnt(3)
	v_cvt_pk_bf16_f32 v34, v200, v201
	s_waitcnt lgkmcnt(2)
	v_cvt_pk_bf16_f32 v35, v202, v203
	s_waitcnt lgkmcnt(1)
	v_cvt_pk_bf16_f32 v36, v204, v205
	v_lshlrev_b64 v[38:39], 11, v[38:39]
	s_waitcnt lgkmcnt(0)
	v_cvt_pk_bf16_f32 v37, v206, v207
	v_lshl_add_u64 v[28:29], v[40:41], 0, v[38:39]
	global_store_dwordx4 v[28:29], v[34:37], off
	s_waitcnt lgkmcnt(0)
	s_branch .LBB0_9
